# NSA pass 3 far tiles: row sum of the 32 exponentials with packed f32 adds (two interleaved partial sums) instead of a 32-deep v_add chain
# baseline (speedup 1.0000x reference)
; #define LAS __attribute__((address_space(3)))
; #define MFMA32(a, b, c) __builtin_amdgcn_mfma_f32_32x32x16_bf16((a), (b), (c), 0, 0, 0)
; __device__ __forceinline__ void tile_soft_far(LAS const unsigned char* ks, LAS const unsigned char* vs, const bf16x8 (&qf)[4], f32x16 (&ot)[2], float& lsum, bool lane_valid, LAS const float* bt, int r, int h) {
;     const float init = lane_valid ? bt[BT_FAR] : -3.0e38f;
;     const int pr = (r & 0x13) | ((r & 4) << 1) | ((r & 8) >> 1);
;     LAS const unsigned char* kp = ks + pr * 144 + h * 16; LAS const unsigned char* vp = vs + r * 144 + h * 16;
;     bf16x8 k0[4], k1[4], v0[2][2], v1[2][2];
; #pragma unroll
;     for (int kk = 0; kk < 4; ++kk) { k0[kk] = *(LAS const bf16x8*)(kp + kk * 32); k1[kk] = *(LAS const bf16x8*)(kp + 32 * 144 + kk * 32); }
;     __builtin_amdgcn_sched_barrier(0);
;     f32x16 s0, s1;
; #pragma unroll
;     for (int i = 0; i < 16; ++i) { s0[i] = init; s1[i] = init; }
; #pragma unroll
;     for (int kk = 0; kk < 4; ++kk) s0 = MFMA32(k0[kk], qf[kk], s0);
; #pragma unroll
;     for (int mt = 0; mt < 2; ++mt)
; #pragma unroll
;         for (int j = 0; j < 2; ++j) { v0[mt][j] = *(LAS const bf16x8*)(vp + 32 * mt * 144 + 32 * j); v1[mt][j] = *(LAS const bf16x8*)(vp + 32 * mt * 144 + 64 + 32 * j); }
;     __builtin_amdgcn_sched_barrier(0);
;     s1 = MFMA32(k1[0], qf[0], s1); SOFT4(s0, 0);  __builtin_amdgcn_sched_barrier(0);
;     s1 = MFMA32(k1[1], qf[1], s1); SOFT4(s0, 4);  __builtin_amdgcn_sched_barrier(0);
;     s1 = MFMA32(k1[2], qf[2], s1); SOFT4(s0, 8);  __builtin_amdgcn_sched_barrier(0);
;     s1 = MFMA32(k1[3], qf[3], s1); SOFT4(s0, 12); __builtin_amdgcn_sched_barrier(0);
;     const bf16x8 pa = pack_p(s0, 0);
;     ot[0] = MFMA32(v0[0][0], pa, ot[0]); SOFT4(s1, 0);  __builtin_amdgcn_sched_barrier(0);
;     ot[1] = MFMA32(v0[1][0], pa, ot[1]); SOFT4(s1, 4);  const bf16x8 pb = pack_p(s0, 1); __builtin_amdgcn_sched_barrier(0);
;     ot[0] = MFMA32(v0[0][1], pb, ot[0]); SOFT4(s1, 8);  __builtin_amdgcn_sched_barrier(0);
;     ot[1] = MFMA32(v0[1][1], pb, ot[1]); SOFT4(s1, 12); __builtin_amdgcn_sched_barrier(0);
; #pragma unroll
;     for (int j = 0; j < 2; ++j) { const bf16x8 pf = pack_p(s1, j); ot[0] = MFMA32(v1[0][j], pf, ot[0]); ot[1] = MFMA32(v1[1][j], pf, ot[1]); }
; }
.Lp3_hw:
	s_cmp_eq_u64 s[6:7], 0
	s_cbranch_scc1 .LBB0_1028
	s_mul_i32 s8, s16, 0x4800
	s_add_i32 s17, s8, 0x100
	s_cmp_le_i32 s15, s11
	s_mov_b64 s[8:9], -1
	s_cbranch_scc0 .LBB0_1025
	v_mov_b32_e32 v64, 0xff61b1e6
	v_cndmask_b32_e64 v64, v64, v234, s[6:7]
	v_add3_u32 v32, s17, v212, v154
	ds_read_b128 v[48:51], v32
	ds_read_b128 v[52:55], v32 offset:32
	ds_read_b128 v[56:59], v32 offset:4608
	ds_read_b128 v[60:63], v32 offset:4640
	ds_read_b128 v[118:121], v32 offset:64
	ds_read_b128 v[160:163], v32 offset:96
	ds_read_b128 v[170:173], v32 offset:4672
	ds_read_b128 v[174:177], v32 offset:4704
	s_waitcnt lgkmcnt(8)
	v_mov_b32_e32 v65, v64
	v_mov_b32_e32 v66, v64
	v_mov_b32_e32 v67, v64
	v_mov_b32_e32 v68, v64
	v_mov_b32_e32 v69, v64
	v_mov_b32_e32 v70, v64
	v_mov_b32_e32 v71, v64
	v_mov_b32_e32 v72, v64
	v_mov_b32_e32 v73, v64
	v_mov_b32_e32 v74, v64
	v_mov_b32_e32 v75, v64
	v_mov_b32_e32 v76, v64
	v_mov_b32_e32 v77, v64
	v_mov_b32_e32 v78, v64
	v_mov_b32_e32 v79, v64
	s_waitcnt lgkmcnt(7)
	s_nop 0
	v_mfma_f32_32x32x16_bf16 v[32:47], v[48:51], v[82:85], v[64:79]
	v_add3_u32 v48, s17, v213, v154
	s_waitcnt lgkmcnt(6)
	v_mfma_f32_32x32x16_bf16 v[32:47], v[52:55], v[86:89], v[32:47]
	s_waitcnt lgkmcnt(3)
	v_mfma_f32_32x32x16_bf16 v[32:47], v[118:121], v[90:93], v[32:47]
	ds_read_b128 v[218:221], v48 offset:9216
	ds_read_b128 v[222:225], v48 offset:9248
	ds_read_b128 v[126:129], v48 offset:9280
	ds_read_b128 v[122:125], v48 offset:9312
	ds_read_b128 v[226:229], v48 offset:13824
	ds_read_b128 v[230:233], v48 offset:13856
	ds_read_b128 v[130:133], v48 offset:13888
	ds_read_b128 v[118:121], v48 offset:13920
	s_waitcnt lgkmcnt(10)
	v_mfma_f32_32x32x16_bf16 v[32:47], v[160:163], v[94:97], v[32:47]
	s_nop 11
	v_exp_f32_e32 v32, v32
	v_exp_f32_e32 v33, v33
	v_exp_f32_e32 v34, v34
	v_exp_f32_e32 v35, v35
	s_nop 0
	v_pk_add_f32 v[244:245], v[32:33], v[34:35]
	v_exp_f32_e32 v36, v36
	v_exp_f32_e32 v37, v37
	v_exp_f32_e32 v38, v38
	v_exp_f32_e32 v39, v39
	v_pk_add_f32 v[244:245], v[244:245], v[36:37]
	v_pk_add_f32 v[244:245], v[244:245], v[38:39]
	v_mfma_f32_32x32x16_bf16 v[64:79], v[56:59], v[82:85], v[64:79]
	v_exp_f32_e32 v178, v40
	v_exp_f32_e32 v179, v41
	v_exp_f32_e32 v180, v42
	v_exp_f32_e32 v181, v43
	v_pk_add_f32 v[244:245], v[244:245], v[178:179]
	v_pk_add_f32 v[244:245], v[244:245], v[180:181]
	v_mfma_f32_32x32x16_bf16 v[64:79], v[60:63], v[86:89], v[64:79]
	v_exp_f32_e32 v240, v44
	s_waitcnt lgkmcnt(9)
	v_mfma_f32_32x32x16_bf16 v[64:79], v[170:173], v[90:93], v[64:79]
	v_exp_f32_e32 v241, v45
	v_exp_f32_e32 v242, v46
	v_exp_f32_e32 v243, v47
	v_pk_add_f32 v[244:245], v[244:245], v[240:241]
	v_pk_add_f32 v[244:245], v[244:245], v[242:243]
	s_waitcnt lgkmcnt(8)
	v_mfma_f32_32x32x16_bf16 v[64:79], v[174:177], v[94:97], v[64:79]
	v_cvt_pk_bf16_f32 v160, v32, v33
	v_cvt_pk_bf16_f32 v161, v34, v35
	v_cvt_pk_bf16_f32 v162, v36, v37
	v_cvt_pk_bf16_f32 v163, v38, v39
	s_nop 7
	v_exp_f32_e32 v246, v64
	v_exp_f32_e32 v247, v65
	s_waitcnt lgkmcnt(7)
	v_mfma_f32_32x32x16_bf16 v[16:31], v[218:221], v[160:163], v[16:31]
	v_exp_f32_e32 v248, v66
	v_exp_f32_e32 v249, v67
	v_pk_add_f32 v[244:245], v[244:245], v[246:247]
	v_pk_add_f32 v[244:245], v[244:245], v[248:249]
	v_exp_f32_e32 v68, v68
	v_exp_f32_e32 v69, v69
	s_waitcnt lgkmcnt(3)
	v_mfma_f32_32x32x16_bf16 v[0:15], v[226:229], v[160:163], v[0:15]
	v_exp_f32_e32 v70, v70
	v_exp_f32_e32 v71, v71
	v_pk_add_f32 v[244:245], v[244:245], v[68:69]
	v_pk_add_f32 v[244:245], v[244:245], v[70:71]
	v_cvt_pk_bf16_f32 v64, v178, v179
	v_cvt_pk_bf16_f32 v65, v180, v181
	v_cvt_pk_bf16_f32 v66, v240, v241
	v_cvt_pk_bf16_f32 v67, v242, v243
	s_nop 1
	v_mfma_f32_32x32x16_bf16 v[16:31], v[222:225], v[64:67], v[16:31]
	v_exp_f32_e32 v72, v72
	v_exp_f32_e32 v73, v73
	v_exp_f32_e32 v74, v74
	v_exp_f32_e32 v75, v75
	v_pk_add_f32 v[244:245], v[244:245], v[72:73]
	v_pk_add_f32 v[244:245], v[244:245], v[74:75]
	s_waitcnt lgkmcnt(2)
	v_mfma_f32_32x32x16_bf16 v[0:15], v[230:233], v[64:67], v[0:15]
	v_exp_f32_e32 v76, v76
	v_exp_f32_e32 v77, v77
	v_exp_f32_e32 v78, v78
	v_exp_f32_e32 v79, v79
	v_pk_add_f32 v[244:245], v[244:245], v[76:77]
	v_pk_add_f32 v[244:245], v[244:245], v[78:79]
	v_add_f32_e32 v160, v244, v245
	v_add_f32_e32 v160, v137, v160
	v_cvt_pk_bf16_f32 v64, v246, v247
	v_cvt_pk_bf16_f32 v65, v248, v249
	v_cvt_pk_bf16_f32 v66, v68, v69
	v_cvt_pk_bf16_f32 v67, v70, v71
	s_mov_b64 s[8:9], 0
	s_nop 0
	v_mfma_f32_32x32x16_bf16 v[16:31], v[126:129], v[64:67], v[16:31]
	s_waitcnt lgkmcnt(1)
	v_mfma_f32_32x32x16_bf16 v[0:15], v[130:133], v[64:67], v[0:15]
	v_cvt_pk_bf16_f32 v64, v72, v73
	v_cvt_pk_bf16_f32 v65, v74, v75
	v_cvt_pk_bf16_f32 v66, v76, v77
	v_cvt_pk_bf16_f32 v67, v78, v79
	s_nop 1
	v_mfma_f32_32x32x16_bf16 v[16:31], v[122:125], v[64:67], v[16:31]
	s_waitcnt lgkmcnt(0)
	v_mfma_f32_32x32x16_bf16 v[0:15], v[118:121], v[64:67], v[0:15]

; __global__ void __launch_bounds__(512, 2) hybrid_fwd(Params P) {
;     ...
;         grid.sync();
;         { PHASE_BEGIN
;             for (int it = bx; it < 256; it += G)
;                 for (int i = 0; i < 4; ++i) { int tidu = tid; asm volatile("" : "+v"(tidu));
;                     branch_tile(lds, (const bf16_t*)(ws + WS_H), (const bf16_t*)(ws + WS_WBR), (const bf16_t*)(ws + WS_A), (bf16_t*)(ws + WS_B), it >> 1, 4 * (it & 1) + i, tidu); }
.LBB0_1085:
	s_nop 0
	s_nop 0
	s_nop 0
	s_nop 0
	s_nop 0
	s_nop 0
	s_nop 0
	s_nop 0
	s_nop 0
	s_nop 0
	s_or_b64 exec, exec, s[4:5]
	s_mov_b32 s4, s34
	s_barrier
	s_mov_b64 s[4:5], s[58:59]
	s_mov_b32 s16, s69
	s_mov_b32 s17, s2
	v_mov_b32_e32 v138, v146
	s_cmpk_gt_i32 s17, 0xff
	s_cbranch_scc1 .LBB0_1096
	s_add_u32 s18, s4, 0x3100000
	s_addc_u32 s19, s5, 0
	s_add_u32 s20, s4, 0xd00000
	s_addc_u32 s21, s5, 0
	s_add_u32 s6, s4, 0x7100000
	s_addc_u32 s7, s5, 0
	s_add_u32 s8, s4, 0x13100000
	s_addc_u32 s9, s5, 0
	s_branch .LBB0_1088
